# all three GEMM K-loops: LDS-DMA loads with SGPR-base addressing + hoisted LDS fragment-read bases (no VALU address math in the load segments)
# speedup vs baseline: 1.0109x; 1.0109x over previous
; #define PG8_STAGE(bufoff, gbase, voff) do { _Pragma("unroll") for (int _i = 0; _i < 2; ++_i) \
;         __builtin_amdgcn_global_load_lds((const unsigned*)((const char*)(gbase) + (voff)[_i]), (PG8_LAS unsigned*)(lds + (bufoff) + ldsw + _i * 8192), 16, 0, 0); } while (0)
; #define PG8_LDA(dst, b, h) do { _Pragma("unroll") for (int m = 0; m < 4; ++m) _Pragma("unroll") for (int k = 0; k < 2; ++k) dst[m][k] = *(const PG8_LAS bf16x8*)(lds + PG8_SA(b, h) + aoff + m * 2048 + k * 1024); } while (0)
; #define PG8_LDB(dst, b, h) do { _Pragma("unroll") for (int n = 0; n < 2; ++n) _Pragma("unroll") for (int k = 0; k < 2; ++k) dst[n][k] = *(const PG8_LAS bf16x8*)(lds + PG8_SB(b, h) + boff + n * 2048 + k * 1024); } while (0)
; #define PG8_WAIT_V(n) asm volatile("s_waitcnt vmcnt(" #n ")" ::: "memory")
; #define PG8_WAIT_L(n) asm volatile("s_waitcnt lgkmcnt(" #n ")" ::: "memory")
; #define PG8_BAR __builtin_amdgcn_s_barrier()
; template <class Epi, class Sched, bool ALIGN_EPI = false, bool SP2 = false>
; __device__ __forceinline__ void gemm_phase(PG8_LAS unsigned char* lds, const Gemm g, const Sched& S, const Epi& E) {
;     ...
;         const bool has_next = S.next(ui + 1, nxt);
;         const char* nA = has_next ? (const char*)g.A + (size_t)nxt.pm * tstep : cA; const char* nB = has_next ? (const char*)g.Bt + (size_t)nxt.pn * tstep : cB;
;         for (int t = 0; t < nt; t += 2) {
;             const bool last = (t == nt - 2);
;             const char* a1 = cA + (size_t)(t + 1) * kstep;
;             const char* a2 = last ? nA : cA + (size_t)(t + 2) * kstep; const char* b2 = last ? nB : cB + (size_t)(t + 2) * kstep;
;             const char* a3 = a2 + kstep; const char* b3 = b2 + kstep;
;             if (last && has_next) S.a_ready(nxt);
;             if constexpr (SP2) {
;             PG8_LDB(B0, 0, 0); PG8_LDB(B1, 0, 1); PG8_SCHED; PG8_LDA(At, 0, 0); PG8_STAGE(PG8_SA(1, 1), a1 + hstep, voffA);
;             PG8_WAIT_V(8); PG8_WAIT_L(0); PG8_BAR; PG8_MMA(0, 0, At, B0); PG8_MMA(0, 1, At, B1); PG8_BAR; PG8_SCHED;
;     ...
; #pragma unroll
;         for (int a = 0; a < 2; ++a)
; #pragma unroll
;             for (int b = 0; b < 2; ++b)
; #pragma unroll
;                 for (int m = 0; m < 4; ++m)
; #pragma unroll
;                     for (int n = 0; n < 2; ++n) acc[a][b][m][n] = (f32x4){0.f, 0.f, 0.f, 0.f};
;         cur = nxt; cA = nA; cB = nB; ++ui;
.LBB0_81:
	s_ashr_i32 s65, s64, 31
	s_lshl_b64 s[28:29], s[64:65], s63
	s_add_u32 s66, s21, s28
	s_addc_u32 s67, s20, s29
	s_and_b64 s[28:29], s[42:43], exec
	s_cselect_b32 s65, s67, s45
	s_cselect_b32 s92, s66, s44
	s_ashr_i32 s61, s60, 31
	s_lshl_b64 s[28:29], s[60:61], s63
	v_readlane_b32 s12, v255, 27
	s_add_u32 s88, s12, s28
	s_addc_u32 s89, s62, s29
	s_and_b64 s[28:29], s[42:43], exec
	s_cselect_b32 s61, s89, s47
	s_cselect_b32 s93, s88, s46
	s_add_u32 s44, s44, 0x80
	s_addc_u32 s45, s45, 0
	s_add_u32 vcc_lo, s46, 0x100
	v_mov_b32_e32 v0, 0
	s_addc_u32 vcc_hi, s47, 0
	s_mov_b32 s46, 0
	v_mov_b32_e32 v1, v0
	v_mov_b32_e32 v2, v0
	v_mov_b32_e32 v3, v0
	v_mov_b32_e32 v4, v0
	v_mov_b32_e32 v5, v0
	v_mov_b32_e32 v6, v0
	v_mov_b32_e32 v7, v0
	v_mov_b32_e32 v16, v0
	v_mov_b32_e32 v17, v0
	v_mov_b32_e32 v18, v0
	v_mov_b32_e32 v19, v0
	v_mov_b32_e32 v20, v0
	v_mov_b32_e32 v21, v0
	v_mov_b32_e32 v22, v0
	v_mov_b32_e32 v23, v0
	v_mov_b32_e32 v32, v0
	v_mov_b32_e32 v33, v0
	v_mov_b32_e32 v34, v0
	v_mov_b32_e32 v35, v0
	v_mov_b32_e32 v36, v0
	v_mov_b32_e32 v37, v0
	v_mov_b32_e32 v38, v0
	v_mov_b32_e32 v39, v0
	v_mov_b32_e32 v48, v0
	v_mov_b32_e32 v49, v0
	v_mov_b32_e32 v50, v0
	v_mov_b32_e32 v51, v0
	v_mov_b32_e32 v52, v0
	v_mov_b32_e32 v53, v0
	v_mov_b32_e32 v54, v0
	v_mov_b32_e32 v55, v0
	v_mov_b32_e32 v8, v0
	v_mov_b32_e32 v9, v0
	v_mov_b32_e32 v10, v0
	v_mov_b32_e32 v11, v0
	v_mov_b32_e32 v12, v0
	v_mov_b32_e32 v13, v0
	v_mov_b32_e32 v14, v0
	v_mov_b32_e32 v15, v0
	v_mov_b32_e32 v24, v0
	v_mov_b32_e32 v25, v0
	v_mov_b32_e32 v26, v0
	v_mov_b32_e32 v27, v0
	v_mov_b32_e32 v28, v0
	v_mov_b32_e32 v29, v0
	v_mov_b32_e32 v30, v0
	v_mov_b32_e32 v31, v0
	v_mov_b32_e32 v40, v0
	v_mov_b32_e32 v41, v0
	v_mov_b32_e32 v42, v0
	v_mov_b32_e32 v43, v0
	v_mov_b32_e32 v44, v0
	v_mov_b32_e32 v45, v0
	v_mov_b32_e32 v46, v0
	v_mov_b32_e32 v47, v0
	v_mov_b32_e32 v72, v0
	v_mov_b32_e32 v73, v0
	v_mov_b32_e32 v74, v0
	v_mov_b32_e32 v75, v0
	v_mov_b32_e32 v76, v0
	v_mov_b32_e32 v77, v0
	v_mov_b32_e32 v78, v0
	v_mov_b32_e32 v79, v0
	v_mov_b32_e32 v80, v0
	v_mov_b32_e32 v81, v0
	v_mov_b32_e32 v82, v0
	v_mov_b32_e32 v83, v0
	v_mov_b32_e32 v84, v0
	v_mov_b32_e32 v85, v0
	v_mov_b32_e32 v86, v0
	v_mov_b32_e32 v87, v0
	v_mov_b32_e32 v96, v0
	v_mov_b32_e32 v97, v0
	v_mov_b32_e32 v98, v0
	v_mov_b32_e32 v99, v0
	v_mov_b32_e32 v100, v0
	v_mov_b32_e32 v101, v0
	v_mov_b32_e32 v102, v0
	v_mov_b32_e32 v103, v0
	v_mov_b32_e32 v112, v0
	v_mov_b32_e32 v113, v0
	v_mov_b32_e32 v114, v0
	v_mov_b32_e32 v115, v0
	v_mov_b32_e32 v116, v0
	v_mov_b32_e32 v117, v0
	v_mov_b32_e32 v118, v0
	v_mov_b32_e32 v119, v0
	v_mov_b32_e32 v128, v0
	v_mov_b32_e32 v129, v0
	v_mov_b32_e32 v130, v0
	v_mov_b32_e32 v131, v0
	v_mov_b32_e32 v132, v0
	v_mov_b32_e32 v133, v0
	v_mov_b32_e32 v134, v0
	v_mov_b32_e32 v135, v0
	v_mov_b32_e32 v88, v0
	v_mov_b32_e32 v89, v0
	v_mov_b32_e32 v90, v0
	v_mov_b32_e32 v91, v0
	v_mov_b32_e32 v92, v0
	v_mov_b32_e32 v93, v0
	v_mov_b32_e32 v94, v0
	v_mov_b32_e32 v95, v0
	v_mov_b32_e32 v104, v0
	v_mov_b32_e32 v105, v0
	v_mov_b32_e32 v106, v0
	v_mov_b32_e32 v107, v0
	v_mov_b32_e32 v108, v0
	v_mov_b32_e32 v109, v0
	v_mov_b32_e32 v110, v0
	v_mov_b32_e32 v111, v0
	v_mov_b32_e32 v120, v0
	v_mov_b32_e32 v121, v0
	v_mov_b32_e32 v122, v0
	v_mov_b32_e32 v123, v0
	v_mov_b32_e32 v124, v0
	v_mov_b32_e32 v125, v0
	v_mov_b32_e32 v126, v0
	v_mov_b32_e32 v127, v0
	v_mov_b32_e32 v136, v0
	v_mov_b32_e32 v137, v0
	v_mov_b32_e32 v138, v0
	v_mov_b32_e32 v139, v0
	v_mov_b32_e32 v140, v0
	v_mov_b32_e32 v141, v0
	v_mov_b32_e32 v142, v0
	v_mov_b32_e32 v143, v0
	s_nop 0
	s_nop 0
	s_nop 0
	s_nop 0
	s_nop 0
	s_nop 0
	s_nop 0
	s_nop 0
	v_add_u32_e32 v204, 0x10000, v235
	v_add_u32_e32 v205, 0x14000, v235
	v_add_u32_e32 v206, 0x18000, v235
	v_add_u32_e32 v207, 0x1c000, v235
.LBB0_82:
	s_add_i32 s28, s46, 2
	s_add_u32 s29, s44, 0x80
	s_addc_u32 s47, s45, 0
	s_add_i32 s12, 0, 0x10000
	s_cmp_eq_u32 s24, s46
	s_cselect_b32 s47, s65, s47
	s_cselect_b32 s46, s92, s29
	s_cselect_b32 s73, s61, vcc_hi
	s_cselect_b32 s72, s93, vcc_lo
	s_add_i32 s29, 0, 0x14000
	ds_read_b128 v[56:59], v204
	ds_read_b128 v[60:63], v204 offset:1024
	ds_read_b128 v[64:67], v204 offset:2048
	ds_read_b128 v[68:71], v204 offset:3072
	ds_read_b128 v[144:147], v205
	ds_read_b128 v[148:151], v205 offset:1024
	ds_read_b128 v[152:155], v205 offset:2048
	ds_read_b128 v[156:159], v205 offset:3072
	s_add_i32 m0, s70, 0xc000
	ds_read_b128 v[160:163], v237
	ds_read_b128 v[164:167], v237 offset:1024
	ds_read_b128 v[168:171], v237 offset:2048
	ds_read_b128 v[172:175], v237 offset:3072
	ds_read_b128 v[186:189], v237 offset:4096
	ds_read_b128 v[190:193], v237 offset:5120
	ds_read_b128 v[196:199], v237 offset:6144
	ds_read_b128 v[200:203], v237 offset:7168
	global_load_lds_dwordx4 v182, s[44:45]
	s_add_i32 m0, s70, 0xe000
	s_nop 0
	global_load_lds_dwordx4 v184, s[44:45]
	s_waitcnt vmcnt(8)
	s_waitcnt lgkmcnt(0)
	s_barrier
; #define PG8_STAGE(bufoff, gbase, voff) do { _Pragma("unroll") for (int _i = 0; _i < 2; ++_i) \
;         __builtin_amdgcn_global_load_lds((const unsigned*)((const char*)(gbase) + (voff)[_i]), (PG8_LAS unsigned*)(lds + (bufoff) + ldsw + _i * 8192), 16, 0, 0); } while (0)
; #define PG8_LDA(dst, b, h) do { _Pragma("unroll") for (int m = 0; m < 4; ++m) _Pragma("unroll") for (int k = 0; k < 2; ++k) dst[m][k] = *(const PG8_LAS bf16x8*)(lds + PG8_SA(b, h) + aoff + m * 2048 + k * 1024); } while (0)
; #define PG8_MMA(ai, bj, At, Bt) do { __builtin_amdgcn_s_setprio(1); _Pragma("unroll") for (int m = 0; m < 4; ++m) _Pragma("unroll") for (int n = 0; n < 2; ++n) _Pragma("unroll") for (int k = 0; k < 2; ++k) \
;         acc[ai][bj][m][n] = __builtin_amdgcn_mfma_f32_16x16x32_bf16(Bt[n][k], At[m][k], acc[ai][bj][m][n], 0, 0, 0); __builtin_amdgcn_s_setprio(0); } while (0)
; #define PG8_WAIT_V(n) asm volatile("s_waitcnt vmcnt(" #n ")" ::: "memory")
; #define PG8_WAIT_L(n) asm volatile("s_waitcnt lgkmcnt(" #n ")" ::: "memory")
; #define PG8_BAR __builtin_amdgcn_s_barrier()
; #define PG8_SCHED __builtin_amdgcn_sched_barrier(0)
; template <class Epi, class Sched, bool ALIGN_EPI = false, bool SP2 = false>
; __device__ __forceinline__ void gemm_phase(PG8_LAS unsigned char* lds, const Gemm g, const Sched& S, const Epi& E) {
;     ...
;             PG8_WAIT_V(8); PG8_WAIT_L(0); PG8_BAR; PG8_MMA(0, 0, At, B0); PG8_MMA(0, 1, At, B1); PG8_BAR; PG8_SCHED;
;             PG8_LDA(At, 0, 1); PG8_STAGE(PG8_SB(0, 0), b2, voffB); PG8_STAGE(PG8_SB(0, 1), b2 + hstep, voffB); PG8_STAGE(PG8_SA(0, 0), a2, voffA);
;             PG8_WAIT_V(8); PG8_WAIT_L(0); PG8_BAR; PG8_MMA(1, 0, At, B0); PG8_MMA(1, 1, At, B1); PG8_BAR; PG8_SCHED;
	s_setprio 1
	s_waitcnt lgkmcnt(0)
	v_mfma_f32_16x16x32_bf16 v[140:143], v[56:59], v[160:163], v[140:143]
	v_mfma_f32_16x16x32_bf16 v[136:139], v[64:67], v[160:163], v[136:139]
	v_mfma_f32_16x16x32_bf16 v[124:127], v[56:59], v[168:171], v[124:127]
	v_mfma_f32_16x16x32_bf16 v[120:123], v[64:67], v[168:171], v[120:123]
	v_mfma_f32_16x16x32_bf16 v[108:111], v[56:59], v[186:189], v[108:111]
	v_mfma_f32_16x16x32_bf16 v[104:107], v[64:67], v[186:189], v[104:107]
	v_mfma_f32_16x16x32_bf16 v[92:95], v[56:59], v[196:199], v[92:95]
	v_mfma_f32_16x16x32_bf16 v[88:91], v[64:67], v[196:199], v[88:91]
	v_mfma_f32_16x16x32_bf16 v[140:143], v[60:63], v[164:167], v[140:143]
	v_mfma_f32_16x16x32_bf16 v[136:139], v[68:71], v[164:167], v[136:139]
	v_mfma_f32_16x16x32_bf16 v[124:127], v[60:63], v[172:175], v[124:127]
	v_mfma_f32_16x16x32_bf16 v[120:123], v[68:71], v[172:175], v[120:123]
	v_mfma_f32_16x16x32_bf16 v[108:111], v[60:63], v[190:193], v[108:111]
	v_mfma_f32_16x16x32_bf16 v[104:107], v[68:71], v[190:193], v[104:107]
	v_mfma_f32_16x16x32_bf16 v[92:95], v[60:63], v[200:203], v[92:95]
	v_mfma_f32_16x16x32_bf16 v[88:91], v[68:71], v[200:203], v[88:91]
	s_setprio 0
	s_setprio 1
	v_mfma_f32_16x16x32_bf16 v[132:135], v[144:147], v[160:163], v[132:135]
	v_mfma_f32_16x16x32_bf16 v[128:131], v[152:155], v[160:163], v[128:131]
	v_mfma_f32_16x16x32_bf16 v[116:119], v[144:147], v[168:171], v[116:119]
	v_mfma_f32_16x16x32_bf16 v[112:115], v[152:155], v[168:171], v[112:115]
	v_mfma_f32_16x16x32_bf16 v[100:103], v[144:147], v[186:189], v[100:103]
	v_mfma_f32_16x16x32_bf16 v[96:99], v[152:155], v[186:189], v[96:99]
	v_mfma_f32_16x16x32_bf16 v[84:87], v[144:147], v[196:199], v[84:87]
	v_mfma_f32_16x16x32_bf16 v[80:83], v[152:155], v[196:199], v[80:83]
	v_mfma_f32_16x16x32_bf16 v[132:135], v[148:151], v[164:167], v[132:135]
	v_mfma_f32_16x16x32_bf16 v[128:131], v[156:159], v[164:167], v[128:131]
	v_mfma_f32_16x16x32_bf16 v[116:119], v[148:151], v[172:175], v[116:119]
	v_mfma_f32_16x16x32_bf16 v[112:115], v[156:159], v[172:175], v[112:115]
	v_mfma_f32_16x16x32_bf16 v[100:103], v[148:151], v[190:193], v[100:103]
	v_mfma_f32_16x16x32_bf16 v[96:99], v[156:159], v[190:193], v[96:99]
	v_mfma_f32_16x16x32_bf16 v[84:87], v[148:151], v[200:203], v[84:87]
	v_mfma_f32_16x16x32_bf16 v[80:83], v[156:159], v[200:203], v[80:83]
	s_setprio 0
	s_barrier
	s_add_i32 s12, s12, s2
	s_mov_b32 m0, s12
	ds_read_b128 v[160:163], v237 offset:16384
	ds_read_b128 v[164:167], v237 offset:17408
	ds_read_b128 v[168:171], v237 offset:18432
	ds_read_b128 v[172:175], v237 offset:19456
	ds_read_b128 v[186:189], v237 offset:20480
	ds_read_b128 v[190:193], v237 offset:21504
	ds_read_b128 v[196:199], v237 offset:22528
	ds_read_b128 v[200:203], v237 offset:23552
	global_load_lds_dwordx4 v194, s[72:73]
	s_add_i32 m0, s12, 0x2000
	s_add_u32 s98, s72, 0x80
	s_addc_u32 s99, s73, 0
	s_add_i32 s12, s29, s2
	global_load_lds_dwordx4 v176, s[72:73]
	s_mov_b32 m0, s12
	s_add_u32 s72, s72, s22
	s_addc_u32 s73, s73, 0
	s_add_u32 s100, s46, 0x80
	s_addc_u32 s101, s47, 0
	global_load_lds_dwordx4 v194, s[72:73]
	s_add_i32 m0, s12, 0x2000
	s_nop 0
	global_load_lds_dwordx4 v176, s[72:73]
	s_mov_b32 m0, s70
	s_nop 0
	global_load_lds_dwordx4 v180, s[46:47]
	s_mov_b32 m0, s71
	s_nop 0
	global_load_lds_dwordx4 v178, s[46:47]
	s_waitcnt vmcnt(8)
	s_waitcnt lgkmcnt(0)
	s_barrier
	s_setprio 1
	s_waitcnt lgkmcnt(0)
	v_mfma_f32_16x16x32_bf16 v[76:79], v[56:59], v[160:163], v[76:79]
	v_mfma_f32_16x16x32_bf16 v[72:75], v[64:67], v[160:163], v[72:75]
	v_mfma_f32_16x16x32_bf16 v[44:47], v[56:59], v[168:171], v[44:47]
	v_mfma_f32_16x16x32_bf16 v[40:43], v[64:67], v[168:171], v[40:43]
	v_mfma_f32_16x16x32_bf16 v[28:31], v[56:59], v[186:189], v[28:31]
	v_mfma_f32_16x16x32_bf16 v[24:27], v[64:67], v[186:189], v[24:27]
	v_mfma_f32_16x16x32_bf16 v[12:15], v[56:59], v[196:199], v[12:15]
	v_mfma_f32_16x16x32_bf16 v[8:11], v[64:67], v[196:199], v[8:11]
	v_mfma_f32_16x16x32_bf16 v[76:79], v[60:63], v[164:167], v[76:79]
	v_mfma_f32_16x16x32_bf16 v[72:75], v[68:71], v[164:167], v[72:75]
	v_mfma_f32_16x16x32_bf16 v[44:47], v[60:63], v[172:175], v[44:47]
	v_mfma_f32_16x16x32_bf16 v[40:43], v[68:71], v[172:175], v[40:43]
	v_mfma_f32_16x16x32_bf16 v[28:31], v[60:63], v[190:193], v[28:31]
	v_mfma_f32_16x16x32_bf16 v[24:27], v[68:71], v[190:193], v[24:27]
	v_mfma_f32_16x16x32_bf16 v[12:15], v[60:63], v[200:203], v[12:15]
	v_mfma_f32_16x16x32_bf16 v[8:11], v[68:71], v[200:203], v[8:11]
	s_setprio 0
	s_setprio 1
	v_mfma_f32_16x16x32_bf16 v[52:55], v[144:147], v[160:163], v[52:55]
	v_mfma_f32_16x16x32_bf16 v[48:51], v[152:155], v[160:163], v[48:51]
	v_mfma_f32_16x16x32_bf16 v[36:39], v[144:147], v[168:171], v[36:39]
	v_mfma_f32_16x16x32_bf16 v[32:35], v[152:155], v[168:171], v[32:35]
	v_mfma_f32_16x16x32_bf16 v[20:23], v[144:147], v[186:189], v[20:23]
	v_mfma_f32_16x16x32_bf16 v[16:19], v[152:155], v[186:189], v[16:19]
	v_mfma_f32_16x16x32_bf16 v[4:7], v[144:147], v[196:199], v[4:7]
	v_mfma_f32_16x16x32_bf16 v[0:3], v[152:155], v[196:199], v[0:3]
	v_mfma_f32_16x16x32_bf16 v[52:55], v[148:151], v[164:167], v[52:55]
	v_mfma_f32_16x16x32_bf16 v[48:51], v[156:159], v[164:167], v[48:51]
	v_mfma_f32_16x16x32_bf16 v[36:39], v[148:151], v[172:175], v[36:39]
	v_mfma_f32_16x16x32_bf16 v[32:35], v[156:159], v[172:175], v[32:35]
	v_mfma_f32_16x16x32_bf16 v[20:23], v[148:151], v[190:193], v[20:23]
	v_mfma_f32_16x16x32_bf16 v[16:19], v[156:159], v[190:193], v[16:19]
	v_mfma_f32_16x16x32_bf16 v[4:7], v[148:151], v[200:203], v[4:7]
	v_mfma_f32_16x16x32_bf16 v[0:3], v[156:159], v[200:203], v[0:3]
	s_setprio 0
	s_barrier
; #define PG8_STAGE(bufoff, gbase, voff) do { _Pragma("unroll") for (int _i = 0; _i < 2; ++_i) \
;         __builtin_amdgcn_global_load_lds((const unsigned*)((const char*)(gbase) + (voff)[_i]), (PG8_LAS unsigned*)(lds + (bufoff) + ldsw + _i * 8192), 16, 0, 0); } while (0)
; #define PG8_LDA(dst, b, h) do { _Pragma("unroll") for (int m = 0; m < 4; ++m) _Pragma("unroll") for (int k = 0; k < 2; ++k) dst[m][k] = *(const PG8_LAS bf16x8*)(lds + PG8_SA(b, h) + aoff + m * 2048 + k * 1024); } while (0)
; #define PG8_LDB(dst, b, h) do { _Pragma("unroll") for (int n = 0; n < 2; ++n) _Pragma("unroll") for (int k = 0; k < 2; ++k) dst[n][k] = *(const PG8_LAS bf16x8*)(lds + PG8_SB(b, h) + boff + n * 2048 + k * 1024); } while (0)
; #define PG8_MMA(ai, bj, At, Bt) do { __builtin_amdgcn_s_setprio(1); _Pragma("unroll") for (int m = 0; m < 4; ++m) _Pragma("unroll") for (int n = 0; n < 2; ++n) _Pragma("unroll") for (int k = 0; k < 2; ++k) \
;         acc[ai][bj][m][n] = __builtin_amdgcn_mfma_f32_16x16x32_bf16(Bt[n][k], At[m][k], acc[ai][bj][m][n], 0, 0, 0); __builtin_amdgcn_s_setprio(0); } while (0)
; #define PG8_WAIT_V(n) asm volatile("s_waitcnt vmcnt(" #n ")" ::: "memory")
; #define PG8_WAIT_L(n) asm volatile("s_waitcnt lgkmcnt(" #n ")" ::: "memory")
; #define PG8_BAR __builtin_amdgcn_s_barrier()
; #define PG8_SCHED __builtin_amdgcn_sched_barrier(0)
; template <class Epi, class Sched, bool ALIGN_EPI = false, bool SP2 = false>
; __device__ __forceinline__ void gemm_phase(PG8_LAS unsigned char* lds, const Gemm g, const Sched& S, const Epi& E) {
;     ...
;             PG8_LDB(B0, 1, 0); PG8_LDB(B1, 1, 1); PG8_SCHED; PG8_LDA(At, 1, 0); PG8_STAGE(PG8_SA(0, 1), a2 + hstep, voffA);
;             PG8_WAIT_V(8); PG8_WAIT_L(0); PG8_BAR; PG8_MMA(0, 0, At, B0); PG8_MMA(0, 1, At, B1); PG8_BAR; PG8_SCHED;
;             PG8_LDA(At, 1, 1); PG8_STAGE(PG8_SB(1, 0), b3, voffB); PG8_STAGE(PG8_SB(1, 1), b3 + hstep, voffB); PG8_STAGE(PG8_SA(1, 0), a3, voffA);
;             PG8_WAIT_V(8); PG8_WAIT_L(0); PG8_BAR; PG8_MMA(1, 0, At, B0); PG8_MMA(1, 1, At, B1); PG8_BAR; PG8_SCHED;
;     ...
;         if constexpr (ALIGN_EPI) { if (wr == 0) PG8_BAR; }
	s_add_i32 s12, 0, 0x18000
	s_add_i32 s29, 0, 0x1c000
	ds_read_b128 v[56:59], v206
	ds_read_b128 v[60:63], v206 offset:1024
	ds_read_b128 v[64:67], v206 offset:2048
	ds_read_b128 v[68:71], v206 offset:3072
	ds_read_b128 v[144:147], v207
	ds_read_b128 v[148:151], v207 offset:1024
	ds_read_b128 v[152:155], v207 offset:2048
	ds_read_b128 v[156:159], v207 offset:3072
	s_add_u32 s46, s46, s22
	s_addc_u32 s47, s47, 0
	s_mov_b32 m0, s76
	ds_read_b128 v[160:163], v237 offset:32768
	ds_read_b128 v[164:167], v237 offset:33792
	ds_read_b128 v[168:171], v237 offset:34816
	ds_read_b128 v[172:175], v237 offset:35840
	ds_read_b128 v[186:189], v237 offset:36864
	ds_read_b128 v[190:193], v237 offset:37888
	ds_read_b128 v[196:199], v237 offset:38912
	ds_read_b128 v[200:203], v237 offset:39936
	global_load_lds_dwordx4 v180, s[46:47]
	s_mov_b32 m0, s77
	s_nop 0
	global_load_lds_dwordx4 v178, s[46:47]
	s_waitcnt vmcnt(8)
	s_waitcnt lgkmcnt(0)
	s_barrier
	s_setprio 1
	s_waitcnt lgkmcnt(0)
	v_mfma_f32_16x16x32_bf16 v[140:143], v[56:59], v[160:163], v[140:143]
	v_mfma_f32_16x16x32_bf16 v[136:139], v[64:67], v[160:163], v[136:139]
	v_mfma_f32_16x16x32_bf16 v[124:127], v[56:59], v[168:171], v[124:127]
	v_mfma_f32_16x16x32_bf16 v[120:123], v[64:67], v[168:171], v[120:123]
	v_mfma_f32_16x16x32_bf16 v[108:111], v[56:59], v[186:189], v[108:111]
	v_mfma_f32_16x16x32_bf16 v[104:107], v[64:67], v[186:189], v[104:107]
	v_mfma_f32_16x16x32_bf16 v[92:95], v[56:59], v[196:199], v[92:95]
	v_mfma_f32_16x16x32_bf16 v[88:91], v[64:67], v[196:199], v[88:91]
	v_mfma_f32_16x16x32_bf16 v[140:143], v[60:63], v[164:167], v[140:143]
	v_mfma_f32_16x16x32_bf16 v[136:139], v[68:71], v[164:167], v[136:139]
	v_mfma_f32_16x16x32_bf16 v[124:127], v[60:63], v[172:175], v[124:127]
	v_mfma_f32_16x16x32_bf16 v[120:123], v[68:71], v[172:175], v[120:123]
	v_mfma_f32_16x16x32_bf16 v[108:111], v[60:63], v[190:193], v[108:111]
	v_mfma_f32_16x16x32_bf16 v[104:107], v[68:71], v[190:193], v[104:107]
	v_mfma_f32_16x16x32_bf16 v[92:95], v[60:63], v[200:203], v[92:95]
	v_mfma_f32_16x16x32_bf16 v[88:91], v[68:71], v[200:203], v[88:91]
	s_setprio 0
	s_setprio 1
	v_mfma_f32_16x16x32_bf16 v[132:135], v[144:147], v[160:163], v[132:135]
	v_mfma_f32_16x16x32_bf16 v[128:131], v[152:155], v[160:163], v[128:131]
	v_mfma_f32_16x16x32_bf16 v[116:119], v[144:147], v[168:171], v[116:119]
	v_mfma_f32_16x16x32_bf16 v[112:115], v[152:155], v[168:171], v[112:115]
	v_mfma_f32_16x16x32_bf16 v[100:103], v[144:147], v[186:189], v[100:103]
	v_mfma_f32_16x16x32_bf16 v[96:99], v[152:155], v[186:189], v[96:99]
	v_mfma_f32_16x16x32_bf16 v[84:87], v[144:147], v[196:199], v[84:87]
	v_mfma_f32_16x16x32_bf16 v[80:83], v[152:155], v[196:199], v[80:83]
	v_mfma_f32_16x16x32_bf16 v[132:135], v[148:151], v[164:167], v[132:135]
	v_mfma_f32_16x16x32_bf16 v[128:131], v[156:159], v[164:167], v[128:131]
	v_mfma_f32_16x16x32_bf16 v[116:119], v[148:151], v[172:175], v[116:119]
	v_mfma_f32_16x16x32_bf16 v[112:115], v[156:159], v[172:175], v[112:115]
	v_mfma_f32_16x16x32_bf16 v[100:103], v[148:151], v[190:193], v[100:103]
	v_mfma_f32_16x16x32_bf16 v[96:99], v[156:159], v[190:193], v[96:99]
	v_mfma_f32_16x16x32_bf16 v[84:87], v[148:151], v[200:203], v[84:87]
	v_mfma_f32_16x16x32_bf16 v[80:83], v[156:159], v[200:203], v[80:83]
	s_setprio 0
	s_barrier
	s_add_i32 s12, s12, s2
	s_mov_b32 m0, s12
	ds_read_b128 v[160:163], v237 offset:49152
	ds_read_b128 v[164:167], v237 offset:50176
	ds_read_b128 v[168:171], v237 offset:51200
	ds_read_b128 v[172:175], v237 offset:52224
	ds_read_b128 v[186:189], v237 offset:53248
	ds_read_b128 v[190:193], v237 offset:54272
	ds_read_b128 v[196:199], v237 offset:55296
	ds_read_b128 v[200:203], v237 offset:56320
	global_load_lds_dwordx4 v194, s[98:99]
	s_add_i32 m0, s12, 0x2000
	s_add_i32 s12, s29, s2
	s_add_u32 s72, s72, 0x80
	s_addc_u32 s73, s73, 0
	global_load_lds_dwordx4 v176, s[98:99]
	s_mov_b32 m0, s12
	s_nop 0
	global_load_lds_dwordx4 v194, s[72:73]
	s_add_i32 m0, s12, 0x2000
	s_nop 0
	global_load_lds_dwordx4 v176, s[72:73]
	s_mov_b32 m0, s48
	s_nop 0
	global_load_lds_dwordx4 v180, s[100:101]
	s_mov_b32 m0, s49
	s_nop 0
	global_load_lds_dwordx4 v178, s[100:101]
	s_waitcnt vmcnt(8)
	s_waitcnt lgkmcnt(0)
	s_barrier
	s_setprio 1
	s_waitcnt lgkmcnt(0)
	v_mfma_f32_16x16x32_bf16 v[76:79], v[56:59], v[160:163], v[76:79]
	v_mfma_f32_16x16x32_bf16 v[72:75], v[64:67], v[160:163], v[72:75]
	v_mfma_f32_16x16x32_bf16 v[44:47], v[56:59], v[168:171], v[44:47]
	v_mfma_f32_16x16x32_bf16 v[40:43], v[64:67], v[168:171], v[40:43]
	v_mfma_f32_16x16x32_bf16 v[28:31], v[56:59], v[186:189], v[28:31]
	v_mfma_f32_16x16x32_bf16 v[24:27], v[64:67], v[186:189], v[24:27]
	v_mfma_f32_16x16x32_bf16 v[12:15], v[56:59], v[196:199], v[12:15]
	v_mfma_f32_16x16x32_bf16 v[8:11], v[64:67], v[196:199], v[8:11]
	v_mfma_f32_16x16x32_bf16 v[76:79], v[60:63], v[164:167], v[76:79]
	v_mfma_f32_16x16x32_bf16 v[72:75], v[68:71], v[164:167], v[72:75]
	v_mfma_f32_16x16x32_bf16 v[44:47], v[60:63], v[172:175], v[44:47]
	v_mfma_f32_16x16x32_bf16 v[40:43], v[68:71], v[172:175], v[40:43]
	v_mfma_f32_16x16x32_bf16 v[28:31], v[60:63], v[190:193], v[28:31]
	v_mfma_f32_16x16x32_bf16 v[24:27], v[68:71], v[190:193], v[24:27]
	v_mfma_f32_16x16x32_bf16 v[12:15], v[60:63], v[200:203], v[12:15]
	v_mfma_f32_16x16x32_bf16 v[8:11], v[68:71], v[200:203], v[8:11]
	s_setprio 0
	s_setprio 1
	v_mfma_f32_16x16x32_bf16 v[52:55], v[144:147], v[160:163], v[52:55]
	v_mfma_f32_16x16x32_bf16 v[48:51], v[152:155], v[160:163], v[48:51]
	v_mfma_f32_16x16x32_bf16 v[36:39], v[144:147], v[168:171], v[36:39]
	v_mfma_f32_16x16x32_bf16 v[32:35], v[152:155], v[168:171], v[32:35]
	v_mfma_f32_16x16x32_bf16 v[20:23], v[144:147], v[186:189], v[20:23]
	v_mfma_f32_16x16x32_bf16 v[16:19], v[152:155], v[186:189], v[16:19]
	v_mfma_f32_16x16x32_bf16 v[4:7], v[144:147], v[196:199], v[4:7]
	v_mfma_f32_16x16x32_bf16 v[0:3], v[152:155], v[196:199], v[0:3]
	v_mfma_f32_16x16x32_bf16 v[52:55], v[148:151], v[164:167], v[52:55]
	v_mfma_f32_16x16x32_bf16 v[48:51], v[156:159], v[164:167], v[48:51]
	v_mfma_f32_16x16x32_bf16 v[36:39], v[148:151], v[172:175], v[36:39]
	v_mfma_f32_16x16x32_bf16 v[32:35], v[156:159], v[172:175], v[32:35]
	v_mfma_f32_16x16x32_bf16 v[20:23], v[148:151], v[190:193], v[20:23]
	v_mfma_f32_16x16x32_bf16 v[16:19], v[156:159], v[190:193], v[16:19]
	v_mfma_f32_16x16x32_bf16 v[4:7], v[148:151], v[200:203], v[4:7]
	v_mfma_f32_16x16x32_bf16 v[0:3], v[156:159], v[200:203], v[0:3]
	s_setprio 0
	s_barrier
	s_add_u32 s44, s44, 0x100
	s_addc_u32 s45, s45, 0
	s_add_u32 vcc_lo, vcc_lo, 0x100
	s_addc_u32 vcc_hi, vcc_hi, 0
	s_cmp_ge_u32 s28, s7
	s_mov_b32 s46, s28
	s_cbranch_scc0 .LBB0_82
	s_and_b64 vcc, exec, s[50:51]
	s_cbranch_vccz .LBB0_85
	s_barrier

; #define PG8_BAR __builtin_amdgcn_s_barrier()
; template <class Epi, class Sched, bool ALIGN_EPI = false, bool SP2 = false>
; __device__ __forceinline__ void gemm_phase(PG8_LAS unsigned char* lds, const Gemm g, const Sched& S, const Epi& E) {
;     ...
;         if (!has_next) break;
; #pragma unroll
;         for (int a = 0; a < 2; ++a)
; #pragma unroll
;             for (int b = 0; b < 2; ++b)
; #pragma unroll
;                 for (int m = 0; m < 4; ++m)
; #pragma unroll
;                     for (int n = 0; n < 2; ++n) acc[a][b][m][n] = (f32x4){0.f, 0.f, 0.f, 0.f};
;         cur = nxt; cA = nA; cB = nB; ++ui;
;         if constexpr (ALIGN_EPI) { if (wr == 1) PG8_BAR; }
.LBB0_153:
	s_andn2_b64 vcc, exec, s[42:43]
	s_mov_b64 s[42:43], -1
	s_cbranch_vccnz .LBB0_74
	v_readlane_b32 s28, v255, 28
	v_readlane_b32 s29, v255, 29
	s_andn2_b64 vcc, exec, s[28:29]
	s_cbranch_vccnz .LBB0_73
	s_barrier
	s_branch .LBB0_73
	s_nop 0

; #define PG8_STAGE(bufoff, gbase, voff) do { _Pragma("unroll") for (int _i = 0; _i < 2; ++_i) \
;         __builtin_amdgcn_global_load_lds((const unsigned*)((const char*)(gbase) + (voff)[_i]), (PG8_LAS unsigned*)(lds + (bufoff) + ldsw + _i * 8192), 16, 0, 0); } while (0)
; #define PG8_LDA(dst, b, h) do { _Pragma("unroll") for (int m = 0; m < 4; ++m) _Pragma("unroll") for (int k = 0; k < 2; ++k) dst[m][k] = *(const PG8_LAS bf16x8*)(lds + PG8_SA(b, h) + aoff + m * 2048 + k * 1024); } while (0)
; #define PG8_LDB(dst, b, h) do { _Pragma("unroll") for (int n = 0; n < 2; ++n) _Pragma("unroll") for (int k = 0; k < 2; ++k) dst[n][k] = *(const PG8_LAS bf16x8*)(lds + PG8_SB(b, h) + boff + n * 2048 + k * 1024); } while (0)
; #define PG8_WAIT_V(n) asm volatile("s_waitcnt vmcnt(" #n ")" ::: "memory")
; #define PG8_WAIT_L(n) asm volatile("s_waitcnt lgkmcnt(" #n ")" ::: "memory")
; #define PG8_BAR __builtin_amdgcn_s_barrier()
; template <class Epi, class Sched, bool ALIGN_EPI = false, bool SP2 = false>
; __device__ __forceinline__ void gemm_phase(PG8_LAS unsigned char* lds, const Gemm g, const Sched& S, const Epi& E) {
;     ...
;         const bool has_next = S.next(ui + 1, nxt);
;         const char* nA = has_next ? (const char*)g.A + (size_t)nxt.pm * tstep : cA; const char* nB = has_next ? (const char*)g.Bt + (size_t)nxt.pn * tstep : cB;
;         for (int t = 0; t < nt; t += 2) {
;             const bool last = (t == nt - 2);
;             const char* a1 = cA + (size_t)(t + 1) * kstep;
;             const char* a2 = last ? nA : cA + (size_t)(t + 2) * kstep; const char* b2 = last ? nB : cB + (size_t)(t + 2) * kstep;
;             const char* a3 = a2 + kstep; const char* b3 = b2 + kstep;
;             if (last && has_next) S.a_ready(nxt);
;             if constexpr (SP2) {
;             PG8_LDB(B0, 0, 0); PG8_LDB(B1, 0, 1); PG8_SCHED; PG8_LDA(At, 0, 0); PG8_STAGE(PG8_SA(1, 1), a1 + hstep, voffA);
;             PG8_WAIT_V(8); PG8_WAIT_L(0); PG8_BAR; PG8_MMA(0, 0, At, B0); PG8_MMA(0, 1, At, B1); PG8_BAR; PG8_SCHED;
;     ...
; #pragma unroll
;         for (int a = 0; a < 2; ++a)
; #pragma unroll
;             for (int b = 0; b < 2; ++b)
; #pragma unroll
;                 for (int m = 0; m < 4; ++m)
; #pragma unroll
;                     for (int n = 0; n < 2; ++n) acc[a][b][m][n] = (f32x4){0.f, 0.f, 0.f, 0.f};
;         cur = nxt; cA = nA; cB = nB; ++ui;
.LBB0_401:
	s_ashr_i32 s61, s60, 31
	s_lshl_b64 s[28:29], s[60:61], 20
	s_add_u32 s66, s74, s28
	s_addc_u32 s67, s75, s29
	s_and_b64 s[28:29], s[44:45], exec
	s_cselect_b32 s50, s67, s27
	s_cselect_b32 s51, s66, s26
	s_ashr_i32 s55, s54, 31
	s_lshl_b64 s[28:29], s[54:55], 20
	s_add_u32 s64, s70, s28
	s_addc_u32 s65, s71, s29
	s_and_b64 s[28:29], s[44:45], exec
	s_cselect_b32 s52, s65, s47
	s_cselect_b32 s53, s64, s46
	s_add_u32 s26, s26, 0x80080
	s_addc_u32 s27, s27, 0
	s_add_u32 s55, s46, 0x100
	v_mov_b32_e32 v0, 0
	s_addc_u32 s61, s47, 0
	s_mov_b32 s88, -2
	v_mov_b32_e32 v1, v0
	v_mov_b32_e32 v2, v0
	v_mov_b32_e32 v3, v0
	v_mov_b32_e32 v4, v0
	v_mov_b32_e32 v5, v0
	v_mov_b32_e32 v6, v0
	v_mov_b32_e32 v7, v0
	v_mov_b32_e32 v16, v0
	v_mov_b32_e32 v17, v0
	v_mov_b32_e32 v18, v0
	v_mov_b32_e32 v19, v0
	v_mov_b32_e32 v20, v0
	s_waitcnt lgkmcnt(0)
	v_mov_b32_e32 v21, v0
	v_mov_b32_e32 v22, v0
	v_mov_b32_e32 v23, v0
	v_mov_b32_e32 v48, v0
	v_mov_b32_e32 v49, v0
	v_mov_b32_e32 v50, v0
	v_mov_b32_e32 v51, v0
	v_mov_b32_e32 v52, v0
	v_mov_b32_e32 v53, v0
	v_mov_b32_e32 v54, v0
	v_mov_b32_e32 v55, v0
	v_mov_b32_e32 v64, v0
	v_mov_b32_e32 v65, v0
	v_mov_b32_e32 v66, v0
	v_mov_b32_e32 v67, v0
	v_mov_b32_e32 v68, v0
	v_mov_b32_e32 v69, v0
	v_mov_b32_e32 v70, v0
	v_mov_b32_e32 v71, v0
	v_mov_b32_e32 v8, v0
	v_mov_b32_e32 v9, v0
	v_mov_b32_e32 v10, v0
	v_mov_b32_e32 v11, v0
	v_mov_b32_e32 v12, v0
	v_mov_b32_e32 v13, v0
	v_mov_b32_e32 v14, v0
	v_mov_b32_e32 v15, v0
	v_mov_b32_e32 v24, v0
	v_mov_b32_e32 v25, v0
	v_mov_b32_e32 v26, v0
	v_mov_b32_e32 v27, v0
	v_mov_b32_e32 v28, v0
	v_mov_b32_e32 v29, v0
	v_mov_b32_e32 v30, v0
	v_mov_b32_e32 v31, v0
	v_mov_b32_e32 v56, v0
	v_mov_b32_e32 v57, v0
	v_mov_b32_e32 v58, v0
	v_mov_b32_e32 v59, v0
	v_mov_b32_e32 v60, v0
	v_mov_b32_e32 v61, v0
	v_mov_b32_e32 v62, v0
	v_mov_b32_e32 v63, v0
	v_mov_b32_e32 v72, v0
	v_mov_b32_e32 v73, v0
	v_mov_b32_e32 v74, v0
	v_mov_b32_e32 v75, v0
	v_mov_b32_e32 v76, v0
	v_mov_b32_e32 v77, v0
	v_mov_b32_e32 v78, v0
	v_mov_b32_e32 v79, v0
	v_mov_b32_e32 v80, v0
	v_mov_b32_e32 v81, v0
	v_mov_b32_e32 v82, v0
	v_mov_b32_e32 v83, v0
	v_mov_b32_e32 v84, v0
	v_mov_b32_e32 v85, v0
	v_mov_b32_e32 v86, v0
	v_mov_b32_e32 v87, v0
	v_mov_b32_e32 v96, v0
	v_mov_b32_e32 v97, v0
	v_mov_b32_e32 v98, v0
	v_mov_b32_e32 v99, v0
	v_mov_b32_e32 v100, v0
	v_mov_b32_e32 v101, v0
	v_mov_b32_e32 v102, v0
	v_mov_b32_e32 v103, v0
	v_mov_b32_e32 v112, v0
	v_mov_b32_e32 v113, v0
	v_mov_b32_e32 v114, v0
	v_mov_b32_e32 v115, v0
	v_mov_b32_e32 v116, v0
	v_mov_b32_e32 v117, v0
	v_mov_b32_e32 v118, v0
	v_mov_b32_e32 v119, v0
	v_mov_b32_e32 v128, v0
	v_mov_b32_e32 v129, v0
	v_mov_b32_e32 v130, v0
	v_mov_b32_e32 v131, v0
	v_mov_b32_e32 v132, v0
	v_mov_b32_e32 v133, v0
	v_mov_b32_e32 v134, v0
	v_mov_b32_e32 v135, v0
	v_mov_b32_e32 v88, v0
	v_mov_b32_e32 v89, v0
	v_mov_b32_e32 v90, v0
	v_mov_b32_e32 v91, v0
	v_mov_b32_e32 v92, v0
	v_mov_b32_e32 v93, v0
	v_mov_b32_e32 v94, v0
	v_mov_b32_e32 v95, v0
	v_mov_b32_e32 v104, v0
	v_mov_b32_e32 v105, v0
	v_mov_b32_e32 v106, v0
	v_mov_b32_e32 v107, v0
	v_mov_b32_e32 v108, v0
	v_mov_b32_e32 v109, v0
	v_mov_b32_e32 v110, v0
	v_mov_b32_e32 v111, v0
	v_mov_b32_e32 v120, v0
	v_mov_b32_e32 v121, v0
	v_mov_b32_e32 v122, v0
	v_mov_b32_e32 v123, v0
	v_mov_b32_e32 v124, v0
	v_mov_b32_e32 v125, v0
	v_mov_b32_e32 v126, v0
	v_mov_b32_e32 v127, v0
	v_mov_b32_e32 v136, v0
	v_mov_b32_e32 v137, v0
	v_mov_b32_e32 v138, v0
	v_mov_b32_e32 v139, v0
	v_mov_b32_e32 v140, v0
	v_mov_b32_e32 v141, v0
	v_mov_b32_e32 v142, v0
	v_mov_b32_e32 v143, v0
	v_add_u32_e32 v192, 0x10000, v172
	v_add_u32_e32 v193, 0x14000, v172
	v_add_u32_e32 v212, 0x18000, v172
	v_add_u32_e32 v213, 0x1c000, v172
.LBB0_402:
	s_add_u32 s28, s26, 0xfff80080
	s_addc_u32 s29, s27, -1
	s_add_i32 s72, 0, 0x10000
	s_cmp_eq_u32 s88, 28
	s_cselect_b32 s49, s50, s29
	s_cselect_b32 s48, s51, s28
	s_cselect_b32 s47, s52, s61
	s_cselect_b32 s46, s53, s55
	s_add_i32 s73, 0, 0x14000
	ds_read_b128 v[32:35], v192
	ds_read_b128 v[36:39], v192 offset:1024
	ds_read_b128 v[40:43], v192 offset:2048
	ds_read_b128 v[44:47], v192 offset:3072
	ds_read_b128 v[160:163], v193
	ds_read_b128 v[164:167], v193 offset:1024
	ds_read_b128 v[168:171], v193 offset:2048
	ds_read_b128 v[176:179], v193 offset:3072
	s_add_i32 m0, s77, 0xc000
	ds_read_b128 v[180:183], v174
	ds_read_b128 v[184:187], v174 offset:1024
	ds_read_b128 v[188:191], v174 offset:2048
	ds_read_b128 v[196:199], v174 offset:3072
	ds_read_b128 v[200:203], v174 offset:4096
	ds_read_b128 v[204:207], v174 offset:5120
	ds_read_b128 v[208:211], v174 offset:6144
	ds_read_b128 v[234:237], v174 offset:7168
	global_load_lds_dwordx4 v156, s[26:27]
	s_add_i32 m0, s77, 0xe000
	s_nop 0
	global_load_lds_dwordx4 v158, s[26:27]
	s_waitcnt vmcnt(8)
	s_waitcnt lgkmcnt(0)
	s_barrier
; #define PG8_STAGE(bufoff, gbase, voff) do { _Pragma("unroll") for (int _i = 0; _i < 2; ++_i) \
;         __builtin_amdgcn_global_load_lds((const unsigned*)((const char*)(gbase) + (voff)[_i]), (PG8_LAS unsigned*)(lds + (bufoff) + ldsw + _i * 8192), 16, 0, 0); } while (0)
; #define PG8_LDA(dst, b, h) do { _Pragma("unroll") for (int m = 0; m < 4; ++m) _Pragma("unroll") for (int k = 0; k < 2; ++k) dst[m][k] = *(const PG8_LAS bf16x8*)(lds + PG8_SA(b, h) + aoff + m * 2048 + k * 1024); } while (0)
; #define PG8_MMA(ai, bj, At, Bt) do { __builtin_amdgcn_s_setprio(1); _Pragma("unroll") for (int m = 0; m < 4; ++m) _Pragma("unroll") for (int n = 0; n < 2; ++n) _Pragma("unroll") for (int k = 0; k < 2; ++k) \
;         acc[ai][bj][m][n] = __builtin_amdgcn_mfma_f32_16x16x32_bf16(Bt[n][k], At[m][k], acc[ai][bj][m][n], 0, 0, 0); __builtin_amdgcn_s_setprio(0); } while (0)
; #define PG8_WAIT_V(n) asm volatile("s_waitcnt vmcnt(" #n ")" ::: "memory")
; #define PG8_WAIT_L(n) asm volatile("s_waitcnt lgkmcnt(" #n ")" ::: "memory")
; #define PG8_BAR __builtin_amdgcn_s_barrier()
; #define PG8_SCHED __builtin_amdgcn_sched_barrier(0)
; template <class Epi, class Sched, bool ALIGN_EPI = false, bool SP2 = false>
; __device__ __forceinline__ void gemm_phase(PG8_LAS unsigned char* lds, const Gemm g, const Sched& S, const Epi& E) {
;     ...
;             PG8_WAIT_V(8); PG8_WAIT_L(0); PG8_BAR; PG8_MMA(0, 0, At, B0); PG8_MMA(0, 1, At, B1); PG8_BAR; PG8_SCHED;
;             PG8_LDA(At, 0, 1); PG8_STAGE(PG8_SB(0, 0), b2, voffB); PG8_STAGE(PG8_SB(0, 1), b2 + hstep, voffB); PG8_STAGE(PG8_SA(0, 0), a2, voffA);
;             PG8_WAIT_V(8); PG8_WAIT_L(0); PG8_BAR; PG8_MMA(1, 0, At, B0); PG8_MMA(1, 1, At, B1); PG8_BAR; PG8_SCHED;
	s_setprio 1
	s_waitcnt lgkmcnt(0)
	v_mfma_f32_16x16x32_bf16 v[140:143], v[32:35], v[180:183], v[140:143]
	v_mfma_f32_16x16x32_bf16 v[136:139], v[40:43], v[180:183], v[136:139]
	v_mfma_f32_16x16x32_bf16 v[124:127], v[32:35], v[188:191], v[124:127]
	v_mfma_f32_16x16x32_bf16 v[120:123], v[40:43], v[188:191], v[120:123]
	v_mfma_f32_16x16x32_bf16 v[108:111], v[32:35], v[200:203], v[108:111]
	v_mfma_f32_16x16x32_bf16 v[104:107], v[40:43], v[200:203], v[104:107]
	v_mfma_f32_16x16x32_bf16 v[92:95], v[32:35], v[208:211], v[92:95]
	v_mfma_f32_16x16x32_bf16 v[88:91], v[40:43], v[208:211], v[88:91]
	v_mfma_f32_16x16x32_bf16 v[140:143], v[36:39], v[184:187], v[140:143]
	v_mfma_f32_16x16x32_bf16 v[136:139], v[44:47], v[184:187], v[136:139]
	v_mfma_f32_16x16x32_bf16 v[124:127], v[36:39], v[196:199], v[124:127]
	v_mfma_f32_16x16x32_bf16 v[120:123], v[44:47], v[196:199], v[120:123]
	v_mfma_f32_16x16x32_bf16 v[108:111], v[36:39], v[204:207], v[108:111]
	v_mfma_f32_16x16x32_bf16 v[104:107], v[44:47], v[204:207], v[104:107]
	v_mfma_f32_16x16x32_bf16 v[92:95], v[36:39], v[234:237], v[92:95]
	v_mfma_f32_16x16x32_bf16 v[88:91], v[44:47], v[234:237], v[88:91]
	s_setprio 0
	s_setprio 1
	v_mfma_f32_16x16x32_bf16 v[132:135], v[160:163], v[180:183], v[132:135]
	v_mfma_f32_16x16x32_bf16 v[128:131], v[168:171], v[180:183], v[128:131]
	v_mfma_f32_16x16x32_bf16 v[116:119], v[160:163], v[188:191], v[116:119]
	v_mfma_f32_16x16x32_bf16 v[112:115], v[168:171], v[188:191], v[112:115]
	v_mfma_f32_16x16x32_bf16 v[100:103], v[160:163], v[200:203], v[100:103]
	v_mfma_f32_16x16x32_bf16 v[96:99], v[168:171], v[200:203], v[96:99]
	v_mfma_f32_16x16x32_bf16 v[84:87], v[160:163], v[208:211], v[84:87]
	v_mfma_f32_16x16x32_bf16 v[80:83], v[168:171], v[208:211], v[80:83]
	v_mfma_f32_16x16x32_bf16 v[132:135], v[164:167], v[184:187], v[132:135]
	v_mfma_f32_16x16x32_bf16 v[128:131], v[176:179], v[184:187], v[128:131]
	v_mfma_f32_16x16x32_bf16 v[116:119], v[164:167], v[196:199], v[116:119]
	v_mfma_f32_16x16x32_bf16 v[112:115], v[176:179], v[196:199], v[112:115]
	v_mfma_f32_16x16x32_bf16 v[100:103], v[164:167], v[204:207], v[100:103]
	v_mfma_f32_16x16x32_bf16 v[96:99], v[176:179], v[204:207], v[96:99]
	v_mfma_f32_16x16x32_bf16 v[84:87], v[164:167], v[234:237], v[84:87]
	v_mfma_f32_16x16x32_bf16 v[80:83], v[176:179], v[234:237], v[80:83]
	s_setprio 0
	s_barrier
	s_add_i32 s28, s72, s76
	s_mov_b32 m0, s28
	ds_read_b128 v[180:183], v174 offset:16384
	ds_read_b128 v[184:187], v174 offset:17408
	ds_read_b128 v[188:191], v174 offset:18432
	ds_read_b128 v[196:199], v174 offset:19456
	ds_read_b128 v[200:203], v174 offset:20480
	ds_read_b128 v[204:207], v174 offset:21504
	ds_read_b128 v[208:211], v174 offset:22528
	ds_read_b128 v[234:237], v174 offset:23552
	global_load_lds_dwordx4 v148, s[46:47]
	s_add_i32 m0, s28, 0x2000
	s_add_u32 s28, s46, 0x80000
	s_addc_u32 s29, s47, 0
	s_add_i32 s72, s73, s76
	global_load_lds_dwordx4 v144, s[46:47]
	s_mov_b32 m0, s72
	s_nop 0
	global_load_lds_dwordx4 v148, s[28:29]
	s_add_i32 m0, s72, 0x2000
	s_nop 0
	global_load_lds_dwordx4 v144, s[28:29]
	s_mov_b32 m0, s77
	s_nop 0
	global_load_lds_dwordx4 v150, s[48:49]
	s_mov_b32 m0, s79
	s_nop 0
	global_load_lds_dwordx4 v146, s[48:49]
	s_waitcnt vmcnt(8)
	s_waitcnt lgkmcnt(0)
	s_barrier
	s_setprio 1
	s_waitcnt lgkmcnt(0)
	v_mfma_f32_16x16x32_bf16 v[76:79], v[32:35], v[180:183], v[76:79]
	v_mfma_f32_16x16x32_bf16 v[72:75], v[40:43], v[180:183], v[72:75]
	v_mfma_f32_16x16x32_bf16 v[60:63], v[32:35], v[188:191], v[60:63]
	v_mfma_f32_16x16x32_bf16 v[56:59], v[40:43], v[188:191], v[56:59]
	v_mfma_f32_16x16x32_bf16 v[28:31], v[32:35], v[200:203], v[28:31]
	v_mfma_f32_16x16x32_bf16 v[24:27], v[40:43], v[200:203], v[24:27]
	v_mfma_f32_16x16x32_bf16 v[12:15], v[32:35], v[208:211], v[12:15]
	v_mfma_f32_16x16x32_bf16 v[8:11], v[40:43], v[208:211], v[8:11]
	v_mfma_f32_16x16x32_bf16 v[76:79], v[36:39], v[184:187], v[76:79]
	v_mfma_f32_16x16x32_bf16 v[72:75], v[44:47], v[184:187], v[72:75]
	v_mfma_f32_16x16x32_bf16 v[60:63], v[36:39], v[196:199], v[60:63]
	v_mfma_f32_16x16x32_bf16 v[56:59], v[44:47], v[196:199], v[56:59]
	v_mfma_f32_16x16x32_bf16 v[28:31], v[36:39], v[204:207], v[28:31]
	v_mfma_f32_16x16x32_bf16 v[24:27], v[44:47], v[204:207], v[24:27]
	v_mfma_f32_16x16x32_bf16 v[12:15], v[36:39], v[234:237], v[12:15]
	v_mfma_f32_16x16x32_bf16 v[8:11], v[44:47], v[234:237], v[8:11]
	s_setprio 0
	s_setprio 1
	v_mfma_f32_16x16x32_bf16 v[20:23], v[160:163], v[200:203], v[20:23]
	v_mfma_f32_16x16x32_bf16 v[16:19], v[168:171], v[200:203], v[16:19]
	v_mfma_f32_16x16x32_bf16 v[4:7], v[160:163], v[208:211], v[4:7]
	v_mfma_f32_16x16x32_bf16 v[0:3], v[168:171], v[208:211], v[0:3]
	v_mfma_f32_16x16x32_bf16 v[32:35], v[160:163], v[180:183], v[68:71]
	v_mfma_f32_16x16x32_bf16 v[36:39], v[168:171], v[180:183], v[64:67]
	v_mfma_f32_16x16x32_bf16 v[40:43], v[160:163], v[188:191], v[52:55]
	v_mfma_f32_16x16x32_bf16 v[44:47], v[168:171], v[188:191], v[48:51]
	v_mfma_f32_16x16x32_bf16 v[20:23], v[164:167], v[204:207], v[20:23]
	v_mfma_f32_16x16x32_bf16 v[16:19], v[176:179], v[204:207], v[16:19]
	v_mfma_f32_16x16x32_bf16 v[4:7], v[164:167], v[234:237], v[4:7]
	v_mfma_f32_16x16x32_bf16 v[0:3], v[176:179], v[234:237], v[0:3]
	v_mfma_f32_16x16x32_bf16 v[32:35], v[164:167], v[184:187], v[32:35]
	v_mfma_f32_16x16x32_bf16 v[36:39], v[176:179], v[184:187], v[36:39]
	v_mfma_f32_16x16x32_bf16 v[40:43], v[164:167], v[196:199], v[40:43]
	v_mfma_f32_16x16x32_bf16 v[44:47], v[176:179], v[196:199], v[44:47]
	s_setprio 0
	s_barrier
; #define PG8_STAGE(bufoff, gbase, voff) do { _Pragma("unroll") for (int _i = 0; _i < 2; ++_i) \
;         __builtin_amdgcn_global_load_lds((const unsigned*)((const char*)(gbase) + (voff)[_i]), (PG8_LAS unsigned*)(lds + (bufoff) + ldsw + _i * 8192), 16, 0, 0); } while (0)
; #define PG8_LDA(dst, b, h) do { _Pragma("unroll") for (int m = 0; m < 4; ++m) _Pragma("unroll") for (int k = 0; k < 2; ++k) dst[m][k] = *(const PG8_LAS bf16x8*)(lds + PG8_SA(b, h) + aoff + m * 2048 + k * 1024); } while (0)
; #define PG8_LDB(dst, b, h) do { _Pragma("unroll") for (int n = 0; n < 2; ++n) _Pragma("unroll") for (int k = 0; k < 2; ++k) dst[n][k] = *(const PG8_LAS bf16x8*)(lds + PG8_SB(b, h) + boff + n * 2048 + k * 1024); } while (0)
; #define PG8_MMA(ai, bj, At, Bt) do { __builtin_amdgcn_s_setprio(1); _Pragma("unroll") for (int m = 0; m < 4; ++m) _Pragma("unroll") for (int n = 0; n < 2; ++n) _Pragma("unroll") for (int k = 0; k < 2; ++k) \
;         acc[ai][bj][m][n] = __builtin_amdgcn_mfma_f32_16x16x32_bf16(Bt[n][k], At[m][k], acc[ai][bj][m][n], 0, 0, 0); __builtin_amdgcn_s_setprio(0); } while (0)
; #define PG8_WAIT_V(n) asm volatile("s_waitcnt vmcnt(" #n ")" ::: "memory")
; #define PG8_WAIT_L(n) asm volatile("s_waitcnt lgkmcnt(" #n ")" ::: "memory")
; #define PG8_BAR __builtin_amdgcn_s_barrier()
; #define PG8_SCHED __builtin_amdgcn_sched_barrier(0)
; template <class Epi, class Sched, bool ALIGN_EPI = false, bool SP2 = false>
; __device__ __forceinline__ void gemm_phase(PG8_LAS unsigned char* lds, const Gemm g, const Sched& S, const Epi& E) {
;     ...
;             PG8_LDB(B0, 1, 0); PG8_LDB(B1, 1, 1); PG8_SCHED; PG8_LDA(At, 1, 0); PG8_STAGE(PG8_SA(0, 1), a2 + hstep, voffA);
;             PG8_WAIT_V(8); PG8_WAIT_L(0); PG8_BAR; PG8_MMA(0, 0, At, B0); PG8_MMA(0, 1, At, B1); PG8_BAR; PG8_SCHED;
;             PG8_LDA(At, 1, 1); PG8_STAGE(PG8_SB(1, 0), b3, voffB); PG8_STAGE(PG8_SB(1, 1), b3 + hstep, voffB); PG8_STAGE(PG8_SA(1, 0), a3, voffA);
;             PG8_WAIT_V(8); PG8_WAIT_L(0); PG8_BAR; PG8_MMA(1, 0, At, B0); PG8_MMA(1, 1, At, B1); PG8_BAR; PG8_SCHED;
;     ...
;         if constexpr (ALIGN_EPI) { if (wr == 0) PG8_BAR; }
	s_add_i32 s72, 0, 0x18000
	s_add_i32 s73, 0, 0x1c000
	ds_read_b128 v[48:51], v212
	ds_read_b128 v[52:55], v212 offset:1024
	ds_read_b128 v[64:67], v212 offset:2048
	ds_read_b128 v[68:71], v212 offset:3072
	ds_read_b128 v[160:163], v213
	ds_read_b128 v[164:167], v213 offset:1024
	ds_read_b128 v[168:171], v213 offset:2048
	ds_read_b128 v[176:179], v213 offset:3072
	s_add_u32 s28, s48, 0x80000
	s_addc_u32 s29, s49, 0
	s_mov_b32 m0, s80
	ds_read_b128 v[180:183], v174 offset:32768
	ds_read_b128 v[184:187], v174 offset:33792
	ds_read_b128 v[188:191], v174 offset:34816
	ds_read_b128 v[196:199], v174 offset:35840
	ds_read_b128 v[200:203], v174 offset:36864
	ds_read_b128 v[204:207], v174 offset:37888
	ds_read_b128 v[208:211], v174 offset:38912
	ds_read_b128 v[234:237], v174 offset:39936
	global_load_lds_dwordx4 v150, s[28:29]
	s_mov_b32 m0, s12
	s_nop 0
	global_load_lds_dwordx4 v146, s[28:29]
	s_waitcnt vmcnt(8)
	s_waitcnt lgkmcnt(0)
	s_barrier
	s_setprio 1
	s_waitcnt lgkmcnt(0)
	v_mfma_f32_16x16x32_bf16 v[140:143], v[48:51], v[180:183], v[140:143]
	v_mfma_f32_16x16x32_bf16 v[136:139], v[64:67], v[180:183], v[136:139]
	v_mfma_f32_16x16x32_bf16 v[124:127], v[48:51], v[188:191], v[124:127]
	v_mfma_f32_16x16x32_bf16 v[120:123], v[64:67], v[188:191], v[120:123]
	v_mfma_f32_16x16x32_bf16 v[108:111], v[48:51], v[200:203], v[108:111]
	v_mfma_f32_16x16x32_bf16 v[104:107], v[64:67], v[200:203], v[104:107]
	v_mfma_f32_16x16x32_bf16 v[92:95], v[48:51], v[208:211], v[92:95]
	v_mfma_f32_16x16x32_bf16 v[88:91], v[64:67], v[208:211], v[88:91]
	v_mfma_f32_16x16x32_bf16 v[140:143], v[52:55], v[184:187], v[140:143]
	v_mfma_f32_16x16x32_bf16 v[136:139], v[68:71], v[184:187], v[136:139]
	v_mfma_f32_16x16x32_bf16 v[124:127], v[52:55], v[196:199], v[124:127]
	v_mfma_f32_16x16x32_bf16 v[120:123], v[68:71], v[196:199], v[120:123]
	v_mfma_f32_16x16x32_bf16 v[108:111], v[52:55], v[204:207], v[108:111]
	v_mfma_f32_16x16x32_bf16 v[104:107], v[68:71], v[204:207], v[104:107]
	v_mfma_f32_16x16x32_bf16 v[92:95], v[52:55], v[234:237], v[92:95]
	v_mfma_f32_16x16x32_bf16 v[88:91], v[68:71], v[234:237], v[88:91]
	s_setprio 0
	s_setprio 1
	v_mfma_f32_16x16x32_bf16 v[132:135], v[160:163], v[180:183], v[132:135]
	v_mfma_f32_16x16x32_bf16 v[128:131], v[168:171], v[180:183], v[128:131]
	v_mfma_f32_16x16x32_bf16 v[116:119], v[160:163], v[188:191], v[116:119]
	v_mfma_f32_16x16x32_bf16 v[112:115], v[168:171], v[188:191], v[112:115]
	v_mfma_f32_16x16x32_bf16 v[100:103], v[160:163], v[200:203], v[100:103]
	v_mfma_f32_16x16x32_bf16 v[96:99], v[168:171], v[200:203], v[96:99]
	v_mfma_f32_16x16x32_bf16 v[84:87], v[160:163], v[208:211], v[84:87]
	v_mfma_f32_16x16x32_bf16 v[80:83], v[168:171], v[208:211], v[80:83]
	v_mfma_f32_16x16x32_bf16 v[132:135], v[164:167], v[184:187], v[132:135]
	v_mfma_f32_16x16x32_bf16 v[128:131], v[176:179], v[184:187], v[128:131]
	v_mfma_f32_16x16x32_bf16 v[116:119], v[164:167], v[196:199], v[116:119]
	v_mfma_f32_16x16x32_bf16 v[112:115], v[176:179], v[196:199], v[112:115]
	v_mfma_f32_16x16x32_bf16 v[100:103], v[164:167], v[204:207], v[100:103]
	v_mfma_f32_16x16x32_bf16 v[96:99], v[176:179], v[204:207], v[96:99]
	v_mfma_f32_16x16x32_bf16 v[84:87], v[164:167], v[234:237], v[84:87]
	v_mfma_f32_16x16x32_bf16 v[80:83], v[176:179], v[234:237], v[80:83]
	s_setprio 0
	s_barrier
	s_add_i32 s28, s72, s76
	s_add_u32 s98, s46, 0x80
	s_addc_u32 s99, s47, 0
	s_mov_b32 m0, s28
	ds_read_b128 v[180:183], v174 offset:49152
	ds_read_b128 v[184:187], v174 offset:50176
	ds_read_b128 v[188:191], v174 offset:51200
	ds_read_b128 v[196:199], v174 offset:52224
	ds_read_b128 v[200:203], v174 offset:53248
	ds_read_b128 v[204:207], v174 offset:54272
	ds_read_b128 v[208:211], v174 offset:55296
	ds_read_b128 v[234:237], v174 offset:56320
	global_load_lds_dwordx4 v148, s[98:99]
	s_add_i32 m0, s28, 0x2000
	s_add_u32 s28, s46, 0x80080
	s_addc_u32 s29, s47, 0
	s_add_i32 s46, s73, s76
	global_load_lds_dwordx4 v144, s[98:99]
	s_mov_b32 m0, s46
	s_add_u32 s100, s48, 0x80
	s_addc_u32 s101, s49, 0
	global_load_lds_dwordx4 v148, s[28:29]
	s_add_i32 m0, s46, 0x2000
	s_nop 0
	global_load_lds_dwordx4 v144, s[28:29]
	s_mov_b32 m0, s78
	s_nop 0
	global_load_lds_dwordx4 v150, s[100:101]
	s_mov_b32 m0, s86
	s_nop 0
	global_load_lds_dwordx4 v146, s[100:101]
	s_waitcnt vmcnt(8)
	s_waitcnt lgkmcnt(0)
	s_barrier
	s_setprio 1
	s_waitcnt lgkmcnt(0)
	v_mfma_f32_16x16x32_bf16 v[76:79], v[48:51], v[180:183], v[76:79]
	v_mfma_f32_16x16x32_bf16 v[72:75], v[64:67], v[180:183], v[72:75]
	v_mfma_f32_16x16x32_bf16 v[60:63], v[48:51], v[188:191], v[60:63]
	v_mfma_f32_16x16x32_bf16 v[56:59], v[64:67], v[188:191], v[56:59]
	v_mfma_f32_16x16x32_bf16 v[28:31], v[48:51], v[200:203], v[28:31]
	v_mfma_f32_16x16x32_bf16 v[24:27], v[64:67], v[200:203], v[24:27]
	v_mfma_f32_16x16x32_bf16 v[12:15], v[48:51], v[208:211], v[12:15]
	v_mfma_f32_16x16x32_bf16 v[8:11], v[64:67], v[208:211], v[8:11]
	v_mfma_f32_16x16x32_bf16 v[76:79], v[52:55], v[184:187], v[76:79]
	v_mfma_f32_16x16x32_bf16 v[72:75], v[68:71], v[184:187], v[72:75]
	v_mfma_f32_16x16x32_bf16 v[60:63], v[52:55], v[196:199], v[60:63]
	v_mfma_f32_16x16x32_bf16 v[56:59], v[68:71], v[196:199], v[56:59]
	v_mfma_f32_16x16x32_bf16 v[28:31], v[52:55], v[204:207], v[28:31]
	v_mfma_f32_16x16x32_bf16 v[24:27], v[68:71], v[204:207], v[24:27]
	v_mfma_f32_16x16x32_bf16 v[12:15], v[52:55], v[234:237], v[12:15]
	v_mfma_f32_16x16x32_bf16 v[8:11], v[68:71], v[234:237], v[8:11]
	s_setprio 0
	s_setprio 1
	v_mfma_f32_16x16x32_bf16 v[32:35], v[160:163], v[180:183], v[32:35]
	v_mfma_f32_16x16x32_bf16 v[68:71], v[164:167], v[184:187], v[32:35]
	v_mfma_f32_16x16x32_bf16 v[32:35], v[168:171], v[180:183], v[36:39]
	v_mfma_f32_16x16x32_bf16 v[64:67], v[176:179], v[184:187], v[32:35]
	v_mfma_f32_16x16x32_bf16 v[32:35], v[160:163], v[188:191], v[40:43]
	v_mfma_f32_16x16x32_bf16 v[52:55], v[164:167], v[196:199], v[32:35]
	v_mfma_f32_16x16x32_bf16 v[32:35], v[168:171], v[188:191], v[44:47]
	v_mfma_f32_16x16x32_bf16 v[20:23], v[160:163], v[200:203], v[20:23]
	v_mfma_f32_16x16x32_bf16 v[16:19], v[168:171], v[200:203], v[16:19]
	v_mfma_f32_16x16x32_bf16 v[4:7], v[160:163], v[208:211], v[4:7]
	v_mfma_f32_16x16x32_bf16 v[0:3], v[168:171], v[208:211], v[0:3]
	v_mfma_f32_16x16x32_bf16 v[48:51], v[176:179], v[196:199], v[32:35]
	v_mfma_f32_16x16x32_bf16 v[20:23], v[164:167], v[204:207], v[20:23]
	v_mfma_f32_16x16x32_bf16 v[16:19], v[176:179], v[204:207], v[16:19]
	v_mfma_f32_16x16x32_bf16 v[4:7], v[164:167], v[234:237], v[4:7]
	v_mfma_f32_16x16x32_bf16 v[0:3], v[176:179], v[234:237], v[0:3]
	s_setprio 0
	s_barrier
	s_add_i32 s88, s88, 2
	s_add_u32 s26, s26, 0x100
	s_addc_u32 s27, s27, 0
	s_add_u32 s55, s55, 0x100
	s_addc_u32 s61, s61, 0
	s_cmp_gt_u32 s88, 29
	s_cbranch_scc0 .LBB0_402
	s_and_b64 vcc, exec, s[22:23]
	s_cbranch_vccz .LBB0_405
	s_barrier

; #define PG8_BAR __builtin_amdgcn_s_barrier()
; template <class Epi, class Sched, bool ALIGN_EPI = false, bool SP2 = false>
; __device__ __forceinline__ void gemm_phase(PG8_LAS unsigned char* lds, const Gemm g, const Sched& S, const Epi& E) {
;     ...
;         if (!has_next) break;
; #pragma unroll
;         for (int a = 0; a < 2; ++a)
; #pragma unroll
;             for (int b = 0; b < 2; ++b)
; #pragma unroll
;                 for (int m = 0; m < 4; ++m)
; #pragma unroll
;                     for (int n = 0; n < 2; ++n) acc[a][b][m][n] = (f32x4){0.f, 0.f, 0.f, 0.f};
;         cur = nxt; cA = nA; cB = nB; ++ui;
;         if constexpr (ALIGN_EPI) { if (wr == 1) PG8_BAR; }
.LBB0_552:
	s_andn2_b64 vcc, exec, s[20:21]
	s_cbranch_vccnz .LBB0_397
	s_barrier
	s_branch .LBB0_397
	s_nop 0
	s_nop 0
	s_nop 0
	s_nop 0
	s_nop 0
	s_nop 0
	s_nop 0
	s_nop 0
	s_nop 0
	s_nop 0
	s_nop 0
	s_nop 0
	s_nop 0
	s_nop 0
	s_nop 0
	s_nop 0
	s_nop 0
	s_nop 0
	s_nop 0
	s_nop 0
	s_nop 0
	s_nop 0
	s_nop 0
	s_nop 0
	s_nop 0
	s_nop 0
	s_nop 0
	s_nop 0
	s_nop 0
	s_nop 0
